# speedup vs baseline: 1.0022x; 1.0022x over previous
; DEV int pi32(int i) { return (i & ~12) | ((i & 4) << 1) | ((i & 8) >> 1); }
; DEV f32x16 mfma(bf16x8 a, bf16x8 b, f32x16 c) { return __builtin_amdgcn_mfma_f32_32x32x16_bf16(a, b, c, 0, 0, 0); }
; template <int MODE, int DQK>
; DEV void flash_half(FlashState& s, f32x16* imp, const bf16x8* qf, const char* st, int kh, int kb, int qpos, float cq,
;                     const float* __restrict__ cumk, bool selbit, float c2, float invl, int r32, int hh, int wqmin_, int wqmax_) {
;   f32x16 S = zero16();
;   const int pr32 = pi32(r32);
;   const char* kp = st + (kh * 32 + pr32) * (DQK * 2);
;   const int kkey = (DQK == 128) ? (pr32 & 15) : ((pr32 >> 1) & 7);
; #pragma unroll
;   for (int ks = 0; ks < DQK / 16; ++ks) { bf16x8 kf = *(const bf16x8*)(kp + (((ks * 2 + hh) ^ kkey) << 4)); S = mfma(kf, qf[ks], S); }
;     ...
;     bool nomask = (kb + 31 <= wqmin_);
;     if (MODE == M_WIN) nomask = nomask && (kb > wqmax_ - 512);
;     if (MODE == M_SLC) nomask = nomask && __all(selbit);
;     if (MODE == M_CMP1 || MODE == M_CMP2 || MODE == M_CMP3) nomask = false;
;     if (nomask) {
; #pragma unroll
;       for (int r = 0; r < 16; ++r) {
;         float v = S[r] * c2;
;         if (MODE == M_FOX) v += (cq - ck[r]) * LOG2E;
;         t[r] = v;
;         tmax = fmaxf(tmax, v);
.LBB0_277:
	s_lshl_b32 s18, s6, 6
	v_cmp_le_i32_e32 vcc, s18, v133
	s_and_saveexec_b64 s[14:15], vcc
	s_cbranch_execz .LBB0_298
	v_lshrrev_b64 v[2:3], s6, v[158:159]
	v_and_b32_e32 v1, 1, v2
	v_cmp_eq_u32_e64 s[8:9], 1, v1
	v_cmp_ne_u32_e32 vcc, 0, v1
	s_cbranch_vccz .LBB0_298
	s_mul_i32 s19, s31, 0x8100
	v_add_u32_e32 v1, s19, v164
	v_add_u32_e32 v184, v1, v165
	ds_read_b128 v[2:5], v184
	v_add_u32_e32 v163, v1, v166
	ds_read_b128 v[6:9], v163
	v_add_u32_e32 v185, v1, v168
	v_add_u32_e32 v186, v1, v169
	v_add_u32_e32 v187, v1, v170
	v_add_u32_e32 v188, v1, v171
	v_add_u32_e32 v189, v1, v172
	v_add_u32_e32 v190, v1, v173
	s_waitcnt lgkmcnt(0)
	v_mfma_f32_32x32x16_bf16 v[80:95], v[2:5], v[96:99], 0
	ds_read_b128 v[2:5], v185
	s_or_b32 s10, s18, 31
	v_cmp_gt_i32_e64 s[6:7], s10, v129
	v_cmp_le_i32_e32 vcc, s10, v129
	v_cndmask_b32_e64 v162, 0, 1, s[8:9]
	v_mfma_f32_32x32x16_bf16 v[80:95], v[6:9], v[100:103], v[80:95]
	ds_read_b128 v[6:9], v186
	s_waitcnt lgkmcnt(1)
	v_mfma_f32_32x32x16_bf16 v[80:95], v[2:5], v[104:107], v[80:95]
	ds_read_b128 v[2:5], v187
	s_waitcnt lgkmcnt(1)
	v_mfma_f32_32x32x16_bf16 v[80:95], v[6:9], v[108:111], v[80:95]
	ds_read_b128 v[6:9], v188
	s_waitcnt lgkmcnt(1)
	v_mfma_f32_32x32x16_bf16 v[80:95], v[2:5], v[112:115], v[80:95]
	ds_read_b128 v[2:5], v189
	s_waitcnt lgkmcnt(1)
	v_mfma_f32_32x32x16_bf16 v[80:95], v[6:9], v[116:119], v[80:95]
	ds_read_b128 v[6:9], v190
	s_waitcnt lgkmcnt(1)
	v_mfma_f32_32x32x16_bf16 v[80:95], v[2:5], v[120:123], v[80:95]
	s_waitcnt lgkmcnt(0)
	v_mfma_f32_32x32x16_bf16 v[80:95], v[6:9], v[124:127], v[80:95]
	s_and_saveexec_b64 s[10:11], vcc
	s_cbranch_execz .LBB0_283
	v_cmp_ne_u32_e32 vcc, 0, v162
	s_cmp_eq_u64 vcc, exec
	s_mov_b64 s[16:17], -1
	s_cbranch_scc0 .LBB0_282
	s_nop 5
	v_mul_f32_e32 v2, s96, v80
	v_mul_f32_e32 v3, s96, v81
	v_mul_f32_e32 v4, s96, v82
	v_mul_f32_e32 v5, s96, v83
	v_max3_f32 v1, v2, s89, v3
	v_max3_f32 v1, v1, v4, v5
	v_mul_f32_e32 v6, s96, v84
	v_mul_f32_e32 v7, s96, v85
	v_mul_f32_e32 v8, s96, v86
	v_mul_f32_e32 v9, s96, v87
	v_max3_f32 v1, v1, v6, v7
	v_max3_f32 v1, v1, v8, v9
	v_mul_f32_e32 v10, s96, v88
	v_mul_f32_e32 v11, s96, v89
	v_mul_f32_e32 v12, s96, v90
	v_mul_f32_e32 v13, s96, v91
	v_max3_f32 v1, v1, v10, v11
	v_max3_f32 v1, v1, v12, v13
	v_mul_f32_e32 v14, s96, v92
	v_mul_f32_e32 v15, s96, v93
	v_mul_f32_e32 v160, s96, v94
	v_mul_f32_e32 v161, s96, v95
	v_max3_f32 v1, v1, v14, v15
	v_max3_f32 v1, v1, v160, v161
	s_mov_b64 s[16:17], 0

; template <int MODE, int DQK>
; DEV void flash_half(FlashState& s, f32x16* imp, const bf16x8* qf, const char* st, int kh, int kb, int qpos, float cq,
;                     const float* __restrict__ cumk, bool selbit, float c2, float invl, int r32, int hh, int wqmin_, int wqmax_) {
;     ...
;   for (int ks = 0; ks < DQK / 16; ++ks) { bf16x8 kf = *(const bf16x8*)(kp + (((ks * 2 + hh) ^ kkey) << 4)); S = mfma(kf, qf[ks], S); }
;   const int kbase = kb + 8 * hh;
;   float pr[16];
;   if (MODE == M_SB) {
;     float lk[16];
;     float Tlo = 0.f, Thi = 0.f;
; #pragma unroll
;     for (int r = 0; r < 16; ++r) {
;       int key = kbase + r + (r >= 8 ? 8 : 0);
;       float z2 = S[r] * c2;
;       float sp2 = fmaxf(z2, 0.f) + lg2(1.f + ex2(-fabsf(z2)));
;       lk[r] = (key < qpos) ? -sp2 : 0.f;
;       if (r < 8) Tlo += lk[r]; else Thi += lk[r];
;     }
;     float Plo = __shfl_xor(Tlo, 32), Phi = __shfl_xor(Thi, 32);
;     float baseLo = s.R + Thi + Phi + (hh == 0 ? Plo : 0.f);
;     float baseHi = s.R + (hh == 0 ? Phi : 0.f);
;     float run = 0.f;
; #pragma unroll
;     for (int r = 7; r >= 0; --r) { pr[r] = (kbase + r < qpos) ? ex2(S[r] * c2 + lk[r] + baseLo + run) : 0.f; run += lk[r]; }
;     run = 0.f;
; #pragma unroll
;     for (int r = 15; r >= 8; --r) { pr[r] = (kbase + r + 8 < qpos) ? ex2(S[r] * c2 + lk[r] + baseHi + run) : 0.f; run += lk[r]; }
;     s.R += Tlo + Thi + Plo + Phi;
;   } else {
;     float t[16];
;     float ck[16];
;     if (MODE == M_FOX) {
;       const float* cl = (const float*)(st + 32768) + kh * 32 + 8 * hh;
;       float4 a0 = *(const float4*)(cl), a1 = *(const float4*)(cl + 4);
;       float4 a2 = *(const float4*)(cl + 16), a3 = *(const float4*)(cl + 20);
;     ...
;   bf16x8 pb[2];
; #pragma unroll
;   for (int m = 0; m < 2; ++m) {
;     uint4 u; u.x = cvtpk_asm(pr[8 * m + 0], pr[8 * m + 1]); u.y = cvtpk_asm(pr[8 * m + 2], pr[8 * m + 3]);
;     u.z = cvtpk_asm(pr[8 * m + 4], pr[8 * m + 5]); u.w = cvtpk_asm(pr[8 * m + 6], pr[8 * m + 7]);
;     pb[m] = *(bf16x8*)&u;
;   }
;   if (MODE != M_CMP3) {
;     const char* vp = st + 16384 + r32 * 128;
;     const int vkey = (r32 >> 1) & 7;
; #pragma unroll
;     for (int dt = 0; dt < 4; ++dt)
; #pragma unroll
;       for (int m = 0; m < 2; ++m) {
;         bf16x8 vf = *(const bf16x8*)(vp + dt * 32 * 128 + (((kh * 4 + m * 2 + hh) ^ vkey) << 4));
;         s.o[dt] = mfma(vf, pb[m], s.o[dt]);
;       }
.LBB0_288:
	v_add_u32_e32 v183, s19, v175
	v_cvt_pk_bf16_f32 v85, v4, v5
	v_cvt_pk_bf16_f32 v5, v12, v13
	v_add_u32_e32 v12, v183, v176
	v_cvt_pk_bf16_f32 v87, v8, v9
	v_cvt_pk_bf16_f32 v4, v10, v11
	ds_read_b128 v[8:11], v12 offset:16384
	v_add_u32_e32 v13, v183, v177
	v_cvt_pk_bf16_f32 v84, v80, v81
	v_cvt_pk_bf16_f32 v86, v6, v7
	v_cvt_pk_bf16_f32 v6, v14, v15
	v_cvt_pk_bf16_f32 v7, v82, v83
	s_or_b32 s16, s18, 63
	s_waitcnt lgkmcnt(0)
	v_mfma_f32_32x32x16_bf16 v[64:79], v[8:11], v[84:87], v[64:79]
	ds_read_b128 v[8:11], v13 offset:16384
	v_cmp_gt_i32_e64 s[6:7], s16, v129
	v_cmp_le_i32_e32 vcc, s16, v129
	s_waitcnt lgkmcnt(0)
	v_mfma_f32_32x32x16_bf16 v[64:79], v[8:11], v[4:7], v[64:79]
	ds_read_b128 v[8:11], v12 offset:20480
	s_waitcnt lgkmcnt(0)
	v_mfma_f32_32x32x16_bf16 v[48:63], v[8:11], v[84:87], v[48:63]
	ds_read_b128 v[8:11], v13 offset:20480
	s_waitcnt lgkmcnt(0)
	v_mfma_f32_32x32x16_bf16 v[48:63], v[8:11], v[4:7], v[48:63]
	ds_read_b128 v[8:11], v12 offset:24576
	s_waitcnt lgkmcnt(0)
	v_mfma_f32_32x32x16_bf16 v[32:47], v[8:11], v[84:87], v[32:47]
	ds_read_b128 v[8:11], v13 offset:24576
	s_waitcnt lgkmcnt(0)
	v_mfma_f32_32x32x16_bf16 v[32:47], v[8:11], v[4:7], v[32:47]
	ds_read_b128 v[8:11], v12 offset:28672
	s_waitcnt lgkmcnt(0)
	v_mfma_f32_32x32x16_bf16 v[16:31], v[8:11], v[84:87], v[16:31]
	ds_read_b128 v[8:11], v13 offset:28672
	s_waitcnt lgkmcnt(0)
	v_mfma_f32_32x32x16_bf16 v[16:31], v[8:11], v[4:7], v[16:31]
	ds_read_b128 v[4:7], v184 offset:8192
	s_waitcnt lgkmcnt(0)
	v_mfma_f32_32x32x16_bf16 v[80:95], v[4:7], v[96:99], 0
	ds_read_b128 v[4:7], v163 offset:8192
	s_waitcnt lgkmcnt(0)
	v_mfma_f32_32x32x16_bf16 v[80:95], v[4:7], v[100:103], v[80:95]
	ds_read_b128 v[4:7], v185 offset:8192
	s_waitcnt lgkmcnt(0)
	v_mfma_f32_32x32x16_bf16 v[80:95], v[4:7], v[104:107], v[80:95]
	ds_read_b128 v[4:7], v186 offset:8192
	s_waitcnt lgkmcnt(0)
	v_mfma_f32_32x32x16_bf16 v[80:95], v[4:7], v[108:111], v[80:95]
	ds_read_b128 v[4:7], v187 offset:8192
	s_waitcnt lgkmcnt(0)
	v_mfma_f32_32x32x16_bf16 v[80:95], v[4:7], v[112:115], v[80:95]
	ds_read_b128 v[4:7], v188 offset:8192
	s_waitcnt lgkmcnt(0)
	v_mfma_f32_32x32x16_bf16 v[80:95], v[4:7], v[116:119], v[80:95]
	ds_read_b128 v[4:7], v189 offset:8192
	s_waitcnt lgkmcnt(0)
	v_mfma_f32_32x32x16_bf16 v[80:95], v[4:7], v[120:123], v[80:95]
	ds_read_b128 v[4:7], v190 offset:8192
	s_waitcnt lgkmcnt(0)
	v_mfma_f32_32x32x16_bf16 v[80:95], v[4:7], v[124:127], v[80:95]
	s_and_saveexec_b64 s[16:17], vcc
	s_cbranch_execz .LBB0_292
	v_cmp_ne_u32_e32 vcc, 0, v162
	s_cmp_eq_u64 vcc, exec
	s_mov_b64 s[18:19], -1
	s_cbranch_scc0 .LBB0_291
	s_nop 5
	v_mul_f32_e32 v4, s96, v80
	v_mul_f32_e32 v5, s96, v81
	v_mul_f32_e32 v6, s96, v82
	v_mul_f32_e32 v7, s96, v83
	v_max3_f32 v8, v4, s89, v5
	v_max3_f32 v10, v8, v6, v7
	v_mul_f32_e32 v8, s96, v84
	v_mul_f32_e32 v9, s96, v85
	s_mov_b64 s[18:19], 0
	v_max3_f32 v12, v10, v8, v9
	v_mul_f32_e32 v10, s96, v86
	v_mul_f32_e32 v11, s96, v87
	s_nop 0
	v_max3_f32 v14, v12, v10, v11
	v_mul_f32_e32 v12, s96, v88
	v_mul_f32_e32 v13, s96, v89
	s_nop 0
	v_max3_f32 v160, v14, v12, v13
	v_mul_f32_e32 v14, s96, v90
	v_mul_f32_e32 v15, s96, v91
	s_nop 0
	v_max3_f32 v162, v160, v14, v15
	v_mul_f32_e32 v160, s96, v92
	v_mul_f32_e32 v161, s96, v93
	s_nop 0
	v_max3_f32 v184, v162, v160, v161
	v_mul_f32_e32 v162, s96, v94
	v_mul_f32_e32 v163, s96, v95
	s_nop 0
	v_max3_f32 v184, v184, v162, v163

; template <int MODE, int DQK>
; DEV void flash_half(FlashState& s, f32x16* imp, const bf16x8* qf, const char* st, int kh, int kb, int qpos, float cq,
;                     const float* __restrict__ cumk, bool selbit, float c2, float invl, int r32, int hh, int wqmin_, int wqmax_) {
;     ...
;     if (nomask) {
; #pragma unroll
;       for (int r = 0; r < 16; ++r) {
;         float v = S[r] * c2;
;         if (MODE == M_FOX) v += (cq - ck[r]) * LOG2E;
;         t[r] = v;
;         tmax = fmaxf(tmax, v);
.LBB0_309:
	s_andn2_saveexec_b64 s[6:7], s[6:7]
	s_cbranch_execz .LBB0_311
	s_nop 6
	v_mul_f32_e32 v2, s96, v80
	v_mul_f32_e32 v3, s96, v81
	v_mul_f32_e32 v4, s96, v82
	v_mul_f32_e32 v5, s96, v83
	v_max3_f32 v1, v2, s89, v3
	v_max3_f32 v1, v1, v4, v5
	v_mul_f32_e32 v6, s96, v84
	v_mul_f32_e32 v7, s96, v85
	v_mul_f32_e32 v8, s96, v86
	v_mul_f32_e32 v9, s96, v87
	v_max3_f32 v1, v1, v6, v7
	v_max3_f32 v1, v1, v8, v9
	v_mul_f32_e32 v10, s96, v88
	v_mul_f32_e32 v11, s96, v89
	v_mul_f32_e32 v12, s96, v90
	v_mul_f32_e32 v13, s96, v91
	v_max3_f32 v1, v1, v10, v11
	v_max3_f32 v1, v1, v12, v13
	v_mul_f32_e32 v14, s96, v92
	v_mul_f32_e32 v15, s96, v93
	v_mul_f32_e32 v160, s96, v94
	v_mul_f32_e32 v161, s96, v95
	v_max3_f32 v1, v1, v14, v15
	v_max3_f32 v1, v1, v160, v161

; template <int MODE, int DQK>
; DEV void flash_half(FlashState& s, f32x16* imp, const bf16x8* qf, const char* st, int kh, int kb, int qpos, float cq,
;                     const float* __restrict__ cumk, bool selbit, float c2, float invl, int r32, int hh, int wqmin_, int wqmax_) {
;     ...
;     if (nomask) {
; #pragma unroll
;       for (int r = 0; r < 16; ++r) {
;         float v = S[r] * c2;
;         if (MODE == M_FOX) v += (cq - ck[r]) * LOG2E;
;         t[r] = v;
;         tmax = fmaxf(tmax, v);
.LBB0_316:
	s_andn2_saveexec_b64 s[6:7], s[6:7]
	s_cbranch_execz .LBB0_318
	s_nop 6
	v_mul_f32_e32 v4, s96, v80
	v_mul_f32_e32 v5, s96, v81
	v_mul_f32_e32 v6, s96, v82
	v_mul_f32_e32 v7, s96, v83
	v_max3_f32 v8, v4, s89, v5
	v_max3_f32 v10, v8, v6, v7
	v_mul_f32_e32 v8, s96, v84
	v_mul_f32_e32 v9, s96, v85
	v_mul_f32_e32 v160, s96, v92
	v_mul_f32_e32 v161, s96, v93
	v_max3_f32 v12, v10, v8, v9
	v_mul_f32_e32 v10, s96, v86
	v_mul_f32_e32 v11, s96, v87
	v_mul_f32_e32 v162, s96, v94
	v_mul_f32_e32 v163, s96, v95
	v_max3_f32 v14, v12, v10, v11
	v_mul_f32_e32 v12, s96, v88
	v_mul_f32_e32 v13, s96, v89
	s_nop 0
	v_max3_f32 v80, v14, v12, v13
	v_mul_f32_e32 v14, s96, v90
	v_mul_f32_e32 v15, s96, v91
	s_nop 0
	v_max3_f32 v80, v80, v14, v15
	v_max3_f32 v80, v80, v160, v161
	v_max3_f32 v184, v80, v162, v163

; DEV int pi32(int i) { return (i & ~12) | ((i & 4) << 1) | ((i & 8) >> 1); }
; DEV f32x16 mfma(bf16x8 a, bf16x8 b, f32x16 c) { return __builtin_amdgcn_mfma_f32_32x32x16_bf16(a, b, c, 0, 0, 0); }
; template <int MODE, int DQK>
; DEV void flash_half(FlashState& s, f32x16* imp, const bf16x8* qf, const char* st, int kh, int kb, int qpos, float cq,
;                     const float* __restrict__ cumk, bool selbit, float c2, float invl, int r32, int hh, int wqmin_, int wqmax_) {
;   f32x16 S = zero16();
;   const int pr32 = pi32(r32);
;   const char* kp = st + (kh * 32 + pr32) * (DQK * 2);
;   const int kkey = (DQK == 128) ? (pr32 & 15) : ((pr32 >> 1) & 7);
; #pragma unroll
;   for (int ks = 0; ks < DQK / 16; ++ks) { bf16x8 kf = *(const bf16x8*)(kp + (((ks * 2 + hh) ^ kkey) << 4)); S = mfma(kf, qf[ks], S); }
;     ...
;     if (nomask) {
; #pragma unroll
;       for (int r = 0; r < 16; ++r) {
;         float v = S[r] * c2;
;         if (MODE == M_FOX) v += (cq - ck[r]) * LOG2E;
;         t[r] = v;
;         tmax = fmaxf(tmax, v);
;       }
;     } else {
; #pragma unroll
;       for (int r = 0; r < 16; ++r) {
;         int key = kbase + r + (r >= 8 ? 8 : 0);
;         bool valid = key <= qpos;
;         if (MODE == M_WIN) valid = valid && (key > qpos - 512);
;         if (MODE == M_SLC) valid = valid && selbit;
;         float v = S[r] * c2;
;         if (MODE == M_FOX) v += (cq - ck[r]) * LOG2E;
;         t[r] = valid ? v : -__builtin_inff();
;         tmax = fmaxf(tmax, t[r]);
;       }
;     }
.LBB0_334:
	s_lshl_b32 s10, s6, 6
	v_cmp_le_i32_e32 vcc, s10, v122
	s_and_saveexec_b64 s[24:25], vcc
	s_cbranch_execz .LBB0_350
	s_mul_i32 s11, s59, 0x8100
	v_add_u32_e32 v1, s11, v138
	v_add_u32_e32 v121, v1, v143
	ds_read_b128 v[2:5], v121
	v_add_u32_e32 v120, v1, v145
	ds_read_b128 v[6:9], v120
	v_add_u32_e32 v164, v1, v147
	v_add_u32_e32 v165, v1, v149
	s_or_b32 s6, s10, 31
	v_cmp_le_i32_e32 vcc, s6, v176
	s_waitcnt lgkmcnt(0)
	v_mfma_f32_32x32x16_bf16 v[80:95], v[2:5], v[108:111], 0
	ds_read_b128 v[2:5], v164
	v_mfma_f32_32x32x16_bf16 v[80:95], v[6:9], v[104:107], v[80:95]
	ds_read_b128 v[6:9], v165
	s_waitcnt lgkmcnt(1)
	v_mfma_f32_32x32x16_bf16 v[80:95], v[2:5], v[100:103], v[80:95]
	s_waitcnt lgkmcnt(0)
	v_mfma_f32_32x32x16_bf16 v[80:95], v[6:9], v[96:99], v[80:95]
	s_and_saveexec_b64 s[6:7], vcc
	s_xor_b64 s[6:7], exec, s[6:7]
	s_cbranch_execz .LBB0_337
	s_nop 8
	v_mul_f32_e32 v2, s88, v80
	v_mul_f32_e32 v3, s88, v81
	v_mul_f32_e32 v4, s88, v82
	v_mul_f32_e32 v5, s88, v83
	v_max3_f32 v1, v2, s89, v3
	v_max3_f32 v1, v1, v4, v5
	v_mul_f32_e32 v6, s88, v84
	v_mul_f32_e32 v7, s88, v85
	v_mul_f32_e32 v8, s88, v86
	v_mul_f32_e32 v9, s88, v87
	v_max3_f32 v1, v1, v6, v7
	v_max3_f32 v1, v1, v8, v9
	v_mul_f32_e32 v10, s88, v88
	v_mul_f32_e32 v11, s88, v89
	v_mul_f32_e32 v12, s88, v90
	v_mul_f32_e32 v13, s88, v91
	v_max3_f32 v1, v1, v10, v11
	v_max3_f32 v1, v1, v12, v13
	v_mul_f32_e32 v14, s88, v92
	v_mul_f32_e32 v15, s88, v93
	v_mul_f32_e32 v118, s88, v94
	v_mul_f32_e32 v119, s88, v95
	v_max3_f32 v1, v1, v14, v15
	v_max3_f32 v1, v1, v118, v119
.LBB0_337:
	s_or_saveexec_b64 s[6:7], s[6:7]
	v_or_b32_e32 v163, s10, v154
	s_xor_b64 exec, exec, s[6:7]
	s_cbranch_execz .LBB0_339
	s_nop 4
	v_mul_f32_e32 v1, 0x3e38aa3b, v80
	v_cmp_le_i32_e32 vcc, v163, v152
	v_or_b32_e32 v6, 3, v163
	v_or_b32_e32 v7, 2, v163
	v_cndmask_b32_e32 v2, v210, v1, vcc
	v_mul_f32_e32 v1, 0x3e38aa3b, v81
	v_cmp_lt_i32_e32 vcc, v163, v152
	v_mul_f32_e32 v4, s88, v82
	v_mul_f32_e32 v5, s88, v83
	v_or_b32_e32 v8, 5, v163
	v_cndmask_b32_e32 v3, v210, v1, vcc
	v_cmp_le_i32_e32 vcc, v6, v115
	v_or_b32_e32 v9, 4, v163
	v_or_b32_e32 v10, 7, v163
	v_cndmask_b32_e32 v5, v210, v5, vcc
	v_cmp_le_i32_e32 vcc, v7, v116
	v_mul_f32_e32 v6, s88, v84
	v_mul_f32_e32 v7, s88, v85
	v_or_b32_e32 v11, 6, v163
	v_cndmask_b32_e32 v4, v210, v4, vcc
	v_cmp_le_i32_e32 vcc, v8, v115
	v_or_b32_e32 v12, 17, v163
	v_or_b32_e32 v13, 16, v163
	v_cndmask_b32_e32 v7, v210, v7, vcc
	v_cmp_le_i32_e32 vcc, v9, v116
	v_mul_f32_e32 v8, s88, v86
	v_mul_f32_e32 v9, s88, v87
	v_or_b32_e32 v14, 19, v163
	v_cndmask_b32_e32 v6, v210, v6, vcc
	v_cmp_le_i32_e32 vcc, v10, v115
	v_max3_f32 v1, v2, s89, v3
	v_or_b32_e32 v15, 18, v163
	v_cndmask_b32_e32 v9, v210, v9, vcc
	v_cmp_le_i32_e32 vcc, v11, v116
	v_mul_f32_e32 v10, s88, v88
	v_mul_f32_e32 v11, s88, v89
	v_max3_f32 v1, v1, v4, v5
	v_cndmask_b32_e32 v8, v210, v8, vcc
	v_cmp_le_i32_e32 vcc, v12, v115
	v_or_b32_e32 v80, 21, v163
	v_max3_f32 v1, v1, v6, v7
	v_cndmask_b32_e32 v11, v210, v11, vcc
	v_cmp_le_i32_e32 vcc, v13, v116
	v_mul_f32_e32 v12, s88, v90
	v_mul_f32_e32 v13, s88, v91
	v_or_b32_e32 v81, 20, v163
	v_cndmask_b32_e32 v10, v210, v10, vcc
	v_cmp_le_i32_e32 vcc, v14, v115
	v_max3_f32 v1, v1, v8, v9
	v_or_b32_e32 v82, 23, v163
	v_cndmask_b32_e32 v13, v210, v13, vcc
	v_cmp_le_i32_e32 vcc, v15, v116
	v_mul_f32_e32 v14, s88, v92
	v_mul_f32_e32 v15, s88, v93
	v_max3_f32 v1, v1, v10, v11
	v_cndmask_b32_e32 v12, v210, v12, vcc
	v_cmp_le_i32_e32 vcc, v80, v115
	v_or_b32_e32 v83, 22, v163
	v_max3_f32 v1, v1, v12, v13
	v_cndmask_b32_e32 v15, v210, v15, vcc
	v_cmp_le_i32_e32 vcc, v81, v116
	v_mul_f32_e32 v80, s88, v94
	v_mul_f32_e32 v81, s88, v95
	s_nop 0
	v_cndmask_b32_e32 v14, v210, v14, vcc
	v_cmp_le_i32_e32 vcc, v82, v115
	v_max3_f32 v1, v1, v14, v15
	s_nop 0
	v_cndmask_b32_e32 v119, v210, v81, vcc
	v_cmp_le_i32_e32 vcc, v83, v116
	s_nop 1
	v_cndmask_b32_e32 v118, v210, v80, vcc
	v_max3_f32 v1, v1, v118, v119

; DEV unsigned cvtpk_asm(float lo, float hi) { unsigned r; asm("v_cvt_pk_bf16_f32 %0, %1, %2" : "=v"(r) : "v"(lo), "v"(hi)); return r; }
; DEV f32x16 mfma(bf16x8 a, bf16x8 b, f32x16 c) { return __builtin_amdgcn_mfma_f32_32x32x16_bf16(a, b, c, 0, 0, 0); }
; template <int MODE, int DQK>
; DEV void flash_half(FlashState& s, f32x16* imp, const bf16x8* qf, const char* st, int kh, int kb, int qpos, float cq,
;                     const float* __restrict__ cumk, bool selbit, float c2, float invl, int r32, int hh, int wqmin_, int wqmax_) {
;     ...
;     if (nomask) {
; #pragma unroll
;       for (int r = 0; r < 16; ++r) {
;         float v = S[r] * c2;
;         if (MODE == M_FOX) v += (cq - ck[r]) * LOG2E;
;         t[r] = v;
;         tmax = fmaxf(tmax, v);
;       }
;     } else {
; #pragma unroll
;       for (int r = 0; r < 16; ++r) {
;         int key = kbase + r + (r >= 8 ? 8 : 0);
;         bool valid = key <= qpos;
;         if (MODE == M_WIN) valid = valid && (key > qpos - 512);
;         if (MODE == M_SLC) valid = valid && selbit;
;         float v = S[r] * c2;
;         if (MODE == M_FOX) v += (cq - ck[r]) * LOG2E;
;         t[r] = valid ? v : -__builtin_inff();
;         tmax = fmaxf(tmax, t[r]);
;       }
;     }
;     ...
;   bf16x8 pb[2];
; #pragma unroll
;   for (int m = 0; m < 2; ++m) {
;     uint4 u; u.x = cvtpk_asm(pr[8 * m + 0], pr[8 * m + 1]); u.y = cvtpk_asm(pr[8 * m + 2], pr[8 * m + 3]);
;     u.z = cvtpk_asm(pr[8 * m + 4], pr[8 * m + 5]); u.w = cvtpk_asm(pr[8 * m + 6], pr[8 * m + 7]);
;     pb[m] = *(bf16x8*)&u;
;   }
;   if (MODE != M_CMP3) {
;     const char* vp = st + 16384 + r32 * 128;
;     const int vkey = (r32 >> 1) & 7;
; #pragma unroll
;     for (int dt = 0; dt < 4; ++dt)
; #pragma unroll
;       for (int m = 0; m < 2; ++m) {
;         bf16x8 vf = *(const bf16x8*)(vp + dt * 32 * 128 + (((kh * 4 + m * 2 + hh) ^ vkey) << 4));
;         s.o[dt] = mfma(vf, pb[m], s.o[dt]);
;       }
.LBB0_342:
	v_add_u32_e32 v162, s11, v155
	v_cvt_pk_bf16_f32 v85, v4, v5
	v_cvt_pk_bf16_f32 v5, v12, v13
	v_add_u32_e32 v12, v162, v156
	v_cvt_pk_bf16_f32 v87, v8, v9
	v_cvt_pk_bf16_f32 v4, v10, v11
	ds_read_b128 v[8:11], v12 offset:16384
	v_add_u32_e32 v13, v162, v157
	v_cvt_pk_bf16_f32 v84, v80, v81
	v_cvt_pk_bf16_f32 v86, v6, v7
	v_cvt_pk_bf16_f32 v6, v14, v15
	v_cvt_pk_bf16_f32 v7, v82, v83
	s_or_b32 s6, s10, 63
	s_waitcnt lgkmcnt(0)
	v_mfma_f32_32x32x16_bf16 v[64:79], v[8:11], v[84:87], v[64:79]
	ds_read_b128 v[8:11], v13 offset:16384
	v_cmp_le_i32_e32 vcc, s6, v176
	s_waitcnt lgkmcnt(0)
	v_mfma_f32_32x32x16_bf16 v[64:79], v[8:11], v[4:7], v[64:79]
	ds_read_b128 v[8:11], v12 offset:20480
	s_waitcnt lgkmcnt(0)
	v_mfma_f32_32x32x16_bf16 v[48:63], v[8:11], v[84:87], v[48:63]
	ds_read_b128 v[8:11], v13 offset:20480
	s_waitcnt lgkmcnt(0)
	v_mfma_f32_32x32x16_bf16 v[48:63], v[8:11], v[4:7], v[48:63]
	ds_read_b128 v[8:11], v12 offset:24576
	s_waitcnt lgkmcnt(0)
	v_mfma_f32_32x32x16_bf16 v[32:47], v[8:11], v[84:87], v[32:47]
	ds_read_b128 v[8:11], v13 offset:24576
	s_waitcnt lgkmcnt(0)
	v_mfma_f32_32x32x16_bf16 v[32:47], v[8:11], v[4:7], v[32:47]
	ds_read_b128 v[8:11], v12 offset:28672
	s_waitcnt lgkmcnt(0)
	v_mfma_f32_32x32x16_bf16 v[16:31], v[8:11], v[84:87], v[16:31]
	ds_read_b128 v[8:11], v13 offset:28672
	s_waitcnt lgkmcnt(0)
	v_mfma_f32_32x32x16_bf16 v[16:31], v[8:11], v[4:7], v[16:31]
	ds_read_b128 v[4:7], v121 offset:4096
	s_waitcnt lgkmcnt(0)
	v_mfma_f32_32x32x16_bf16 v[80:95], v[4:7], v[108:111], 0
	ds_read_b128 v[4:7], v120 offset:4096
	s_waitcnt lgkmcnt(0)
	v_mfma_f32_32x32x16_bf16 v[80:95], v[4:7], v[104:107], v[80:95]
	ds_read_b128 v[4:7], v164 offset:4096
	s_waitcnt lgkmcnt(0)
	v_mfma_f32_32x32x16_bf16 v[80:95], v[4:7], v[100:103], v[80:95]
	ds_read_b128 v[4:7], v165 offset:4096
	s_waitcnt lgkmcnt(0)
	v_mfma_f32_32x32x16_bf16 v[80:95], v[4:7], v[96:99], v[80:95]
	s_and_saveexec_b64 s[6:7], vcc
	s_xor_b64 s[6:7], exec, s[6:7]
	s_cbranch_execz .LBB0_344
	s_nop 8
	v_mul_f32_e32 v4, s88, v80
	v_mul_f32_e32 v5, s88, v81
	v_mul_f32_e32 v6, s88, v82
	v_mul_f32_e32 v7, s88, v83
	v_max3_f32 v8, v4, s89, v5
	v_max3_f32 v10, v8, v6, v7
	v_mul_f32_e32 v8, s88, v84
	v_mul_f32_e32 v9, s88, v85
	v_mul_f32_e32 v118, s88, v92
	v_mul_f32_e32 v119, s88, v93
	v_max3_f32 v12, v10, v8, v9
	v_mul_f32_e32 v10, s88, v86
	v_mul_f32_e32 v11, s88, v87
	v_mul_f32_e32 v120, s88, v94
	v_mul_f32_e32 v121, s88, v95
	v_max3_f32 v14, v12, v10, v11
	v_mul_f32_e32 v12, s88, v88
	v_mul_f32_e32 v13, s88, v89
	s_nop 0
	v_max3_f32 v80, v14, v12, v13
	v_mul_f32_e32 v14, s88, v90
	v_mul_f32_e32 v15, s88, v91
	s_nop 0
	v_max3_f32 v80, v80, v14, v15
	v_max3_f32 v80, v80, v118, v119
	v_max3_f32 v164, v80, v120, v121
.LBB0_344:
	s_andn2_saveexec_b64 s[6:7], s[6:7]
	s_cbranch_execz .LBB0_346
	v_or_b32_e32 v5, 32, v163
	s_nop 5
	v_mul_f32_e32 v4, 0x3e38aa3b, v80
	v_cmp_le_i32_e32 vcc, v5, v152
	v_mul_f32_e32 v6, 0x3e38aa3b, v81
	v_or_b32_e32 v9, 35, v163
	v_cndmask_b32_e32 v4, v210, v4, vcc
	v_cmp_lt_i32_e32 vcc, v5, v152
	v_or_b32_e32 v10, 34, v163
	v_or_b32_e32 v11, 37, v163
	v_cndmask_b32_e32 v5, v210, v6, vcc
	v_mul_f32_e32 v6, s88, v82
	v_mul_f32_e32 v7, s88, v83
	v_cmp_le_i32_e32 vcc, v9, v115
	v_max3_f32 v8, v4, s89, v5
	v_or_b32_e32 v12, 36, v163
	v_cndmask_b32_e32 v7, v210, v7, vcc
	v_cmp_le_i32_e32 vcc, v10, v116
	v_or_b32_e32 v13, 39, v163
	v_or_b32_e32 v14, 38, v163
	v_cndmask_b32_e32 v6, v210, v6, vcc
	v_max3_f32 v10, v8, v6, v7
	v_mul_f32_e32 v8, s88, v84
	v_mul_f32_e32 v9, s88, v85
	v_cmp_le_i32_e32 vcc, v11, v115
	v_or_b32_e32 v15, 49, v163
	v_or_b32_e32 v80, 48, v163
	v_cndmask_b32_e32 v9, v210, v9, vcc
	v_cmp_le_i32_e32 vcc, v12, v116
	v_or_b32_e32 v81, 51, v163
	v_or_b32_e32 v82, 50, v163
	v_cndmask_b32_e32 v8, v210, v8, vcc
	v_max3_f32 v12, v10, v8, v9
	v_mul_f32_e32 v10, s88, v86
	v_mul_f32_e32 v11, s88, v87
	v_cmp_le_i32_e32 vcc, v13, v115
	v_or_b32_e32 v83, 53, v163
	v_or_b32_e32 v84, 52, v163
	v_cndmask_b32_e32 v11, v210, v11, vcc
	v_cmp_le_i32_e32 vcc, v14, v116
	s_nop 1
	v_cndmask_b32_e32 v10, v210, v10, vcc
	v_max3_f32 v14, v12, v10, v11
	v_mul_f32_e32 v12, s88, v88
	v_mul_f32_e32 v13, s88, v89
	v_cmp_le_i32_e32 vcc, v15, v115
	s_nop 1
	v_cndmask_b32_e32 v13, v210, v13, vcc
	v_cmp_le_i32_e32 vcc, v80, v116
	s_nop 1
	v_cndmask_b32_e32 v12, v210, v12, vcc
	v_max3_f32 v80, v14, v12, v13
	v_mul_f32_e32 v14, s88, v90
	v_mul_f32_e32 v15, s88, v91
	v_cmp_le_i32_e32 vcc, v81, v115
	s_nop 1
	v_cndmask_b32_e32 v15, v210, v15, vcc
	v_cmp_le_i32_e32 vcc, v82, v116
	s_nop 1
	v_cndmask_b32_e32 v14, v210, v14, vcc
	v_max3_f32 v82, v80, v14, v15
	v_mul_f32_e32 v80, s88, v92
	v_mul_f32_e32 v81, s88, v93
	v_cmp_le_i32_e32 vcc, v83, v115
	v_or_b32_e32 v83, 55, v163
	s_nop 0
	v_cndmask_b32_e32 v119, v210, v81, vcc
	v_cmp_le_i32_e32 vcc, v84, v116
	v_or_b32_e32 v84, 54, v163
	s_nop 0
	v_cndmask_b32_e32 v118, v210, v80, vcc
	v_mul_f32_e32 v80, s88, v94
	v_mul_f32_e32 v81, s88, v95
	v_cmp_le_i32_e32 vcc, v83, v115
	v_max3_f32 v82, v82, v118, v119
	s_nop 0
	v_cndmask_b32_e32 v121, v210, v81, vcc
	v_cmp_le_i32_e32 vcc, v84, v116
	s_nop 1
	v_cndmask_b32_e32 v120, v210, v80, vcc
	v_max3_f32 v164, v82, v120, v121

; DEV int pi32(int i) { return (i & ~12) | ((i & 4) << 1) | ((i & 8) >> 1); }
; DEV f32x16 mfma(bf16x8 a, bf16x8 b, f32x16 c) { return __builtin_amdgcn_mfma_f32_32x32x16_bf16(a, b, c, 0, 0, 0); }
; template <int MODE, int DQK>
; DEV void flash_half(FlashState& s, f32x16* imp, const bf16x8* qf, const char* st, int kh, int kb, int qpos, float cq,
;                     const float* __restrict__ cumk, bool selbit, float c2, float invl, int r32, int hh, int wqmin_, int wqmax_) {
;   f32x16 S = zero16();
;   const int pr32 = pi32(r32);
;   const char* kp = st + (kh * 32 + pr32) * (DQK * 2);
;   const int kkey = (DQK == 128) ? (pr32 & 15) : ((pr32 >> 1) & 7);
; #pragma unroll
;   for (int ks = 0; ks < DQK / 16; ++ks) { bf16x8 kf = *(const bf16x8*)(kp + (((ks * 2 + hh) ^ kkey) << 4)); S = mfma(kf, qf[ks], S); }
;     ...
;     if (nomask) {
; #pragma unroll
;       for (int r = 0; r < 16; ++r) {
;         float v = S[r] * c2;
;         if (MODE == M_FOX) v += (cq - ck[r]) * LOG2E;
;         t[r] = v;
;         tmax = fmaxf(tmax, v);
;       }
;     } else {
; #pragma unroll
;       for (int r = 0; r < 16; ++r) {
;         int key = kbase + r + (r >= 8 ? 8 : 0);
;         bool valid = key <= qpos;
;         if (MODE == M_WIN) valid = valid && (key > qpos - 512);
;         if (MODE == M_SLC) valid = valid && selbit;
;         float v = S[r] * c2;
;         if (MODE == M_FOX) v += (cq - ck[r]) * LOG2E;
;         t[r] = valid ? v : -__builtin_inff();
;         tmax = fmaxf(tmax, t[r]);
;       }
;     }
.LBB0_358:
	s_lshl_b32 s10, s78, 6
	v_cmp_le_i32_e32 vcc, s10, v122
	s_and_saveexec_b64 s[78:79], vcc
	s_cbranch_execz .LBB0_374
	s_mul_i32 s11, s58, 0x8100
	v_add_u32_e32 v1, s11, v127
	v_add_u32_e32 v117, v1, v133
	ds_read_b128 v[2:5], v117
	v_add_u32_e32 v116, v1, v138
	ds_read_b128 v[6:9], v116
	v_add_u32_e32 v161, v1, v141
	v_add_u32_e32 v162, v1, v143
	s_or_b32 s6, s10, 31
	v_cmp_le_i32_e32 vcc, s6, v176
	s_waitcnt lgkmcnt(0)
	v_mfma_f32_32x32x16_bf16 v[80:95], v[2:5], v[96:99], 0
	ds_read_b128 v[2:5], v161
	v_mfma_f32_32x32x16_bf16 v[80:95], v[6:9], v[100:103], v[80:95]
	ds_read_b128 v[6:9], v162
	s_waitcnt lgkmcnt(1)
	v_mfma_f32_32x32x16_bf16 v[80:95], v[2:5], v[104:107], v[80:95]
	s_waitcnt lgkmcnt(0)
	v_mfma_f32_32x32x16_bf16 v[80:95], v[6:9], v[108:111], v[80:95]
	s_and_saveexec_b64 s[6:7], vcc
	s_xor_b64 s[6:7], exec, s[6:7]
	s_cbranch_execz .LBB0_361
	s_nop 8
	v_mul_f32_e32 v2, s88, v80
	v_mul_f32_e32 v3, s88, v81
	v_mul_f32_e32 v4, s88, v82
	v_mul_f32_e32 v5, s88, v83
	v_max3_f32 v1, v2, s89, v3
	v_max3_f32 v1, v1, v4, v5
	v_mul_f32_e32 v6, s88, v84
	v_mul_f32_e32 v7, s88, v85
	v_mul_f32_e32 v8, s88, v86
	v_mul_f32_e32 v9, s88, v87
	v_max3_f32 v1, v1, v6, v7
	v_max3_f32 v1, v1, v8, v9
	v_mul_f32_e32 v10, s88, v88
	v_mul_f32_e32 v11, s88, v89
	v_mul_f32_e32 v12, s88, v90
	v_mul_f32_e32 v13, s88, v91
	v_max3_f32 v1, v1, v10, v11
	v_max3_f32 v1, v1, v12, v13
	v_mul_f32_e32 v14, s88, v92
	v_mul_f32_e32 v15, s88, v93
	v_mul_f32_e32 v114, s88, v94
	v_mul_f32_e32 v115, s88, v95
	v_max3_f32 v1, v1, v14, v15
	v_max3_f32 v1, v1, v114, v115
.LBB0_361:
	s_or_saveexec_b64 s[6:7], s[6:7]
	v_or_b32_e32 v160, s10, v145
	s_xor_b64 exec, exec, s[6:7]
	s_cbranch_execz .LBB0_363
	s_nop 4
	v_mul_f32_e32 v1, 0x3e38aa3b, v80
	v_cmp_le_i32_e32 vcc, v160, v152
	v_or_b32_e32 v6, 3, v160
	v_or_b32_e32 v7, 2, v160
	v_cndmask_b32_e32 v2, v210, v1, vcc
	v_mul_f32_e32 v1, 0x3e38aa3b, v81
	v_cmp_lt_i32_e32 vcc, v160, v152
	v_mul_f32_e32 v4, s88, v82
	v_mul_f32_e32 v5, s88, v83
	v_or_b32_e32 v8, 5, v160
	v_cndmask_b32_e32 v3, v210, v1, vcc
	v_cmp_le_i32_e32 vcc, v6, v113
	v_or_b32_e32 v9, 4, v160
	v_or_b32_e32 v10, 7, v160
	v_cndmask_b32_e32 v5, v210, v5, vcc
	v_cmp_le_i32_e32 vcc, v7, v112
	v_mul_f32_e32 v6, s88, v84
	v_mul_f32_e32 v7, s88, v85
	v_or_b32_e32 v11, 6, v160
	v_cndmask_b32_e32 v4, v210, v4, vcc
	v_cmp_le_i32_e32 vcc, v8, v113
	v_or_b32_e32 v12, 17, v160
	v_or_b32_e32 v13, 16, v160
	v_cndmask_b32_e32 v7, v210, v7, vcc
	v_cmp_le_i32_e32 vcc, v9, v112
	v_mul_f32_e32 v8, s88, v86
	v_mul_f32_e32 v9, s88, v87
	v_or_b32_e32 v14, 19, v160
	v_cndmask_b32_e32 v6, v210, v6, vcc
	v_cmp_le_i32_e32 vcc, v10, v113
	v_max3_f32 v1, v2, s89, v3
	v_or_b32_e32 v15, 18, v160
	v_cndmask_b32_e32 v9, v210, v9, vcc
	v_cmp_le_i32_e32 vcc, v11, v112
	v_mul_f32_e32 v10, s88, v88
	v_mul_f32_e32 v11, s88, v89
	v_max3_f32 v1, v1, v4, v5
	v_cndmask_b32_e32 v8, v210, v8, vcc
	v_cmp_le_i32_e32 vcc, v12, v113
	v_or_b32_e32 v80, 21, v160
	v_max3_f32 v1, v1, v6, v7
	v_cndmask_b32_e32 v11, v210, v11, vcc
	v_cmp_le_i32_e32 vcc, v13, v112
	v_mul_f32_e32 v12, s88, v90
	v_mul_f32_e32 v13, s88, v91
	v_or_b32_e32 v81, 20, v160
	v_cndmask_b32_e32 v10, v210, v10, vcc
	v_cmp_le_i32_e32 vcc, v14, v113
	v_max3_f32 v1, v1, v8, v9
	v_or_b32_e32 v82, 23, v160
	v_cndmask_b32_e32 v13, v210, v13, vcc
	v_cmp_le_i32_e32 vcc, v15, v112
	v_mul_f32_e32 v14, s88, v92
	v_mul_f32_e32 v15, s88, v93
	v_max3_f32 v1, v1, v10, v11
	v_cndmask_b32_e32 v12, v210, v12, vcc
	v_cmp_le_i32_e32 vcc, v80, v113
	v_or_b32_e32 v83, 22, v160
	v_max3_f32 v1, v1, v12, v13
	v_cndmask_b32_e32 v15, v210, v15, vcc
	v_cmp_le_i32_e32 vcc, v81, v112
	v_mul_f32_e32 v80, s88, v94
	v_mul_f32_e32 v81, s88, v95
	s_nop 0
	v_cndmask_b32_e32 v14, v210, v14, vcc
	v_cmp_le_i32_e32 vcc, v82, v113
	v_max3_f32 v1, v1, v14, v15
	s_nop 0
	v_cndmask_b32_e32 v115, v210, v81, vcc
	v_cmp_le_i32_e32 vcc, v83, v112
	s_nop 1
	v_cndmask_b32_e32 v114, v210, v80, vcc
	v_max3_f32 v1, v1, v114, v115

; DEV unsigned cvtpk_asm(float lo, float hi) { unsigned r; asm("v_cvt_pk_bf16_f32 %0, %1, %2" : "=v"(r) : "v"(lo), "v"(hi)); return r; }
; DEV f32x16 mfma(bf16x8 a, bf16x8 b, f32x16 c) { return __builtin_amdgcn_mfma_f32_32x32x16_bf16(a, b, c, 0, 0, 0); }
; template <int MODE, int DQK>
; DEV void flash_half(FlashState& s, f32x16* imp, const bf16x8* qf, const char* st, int kh, int kb, int qpos, float cq,
;                     const float* __restrict__ cumk, bool selbit, float c2, float invl, int r32, int hh, int wqmin_, int wqmax_) {
;     ...
;     if (nomask) {
; #pragma unroll
;       for (int r = 0; r < 16; ++r) {
;         float v = S[r] * c2;
;         if (MODE == M_FOX) v += (cq - ck[r]) * LOG2E;
;         t[r] = v;
;         tmax = fmaxf(tmax, v);
;       }
;     } else {
; #pragma unroll
;       for (int r = 0; r < 16; ++r) {
;         int key = kbase + r + (r >= 8 ? 8 : 0);
;         bool valid = key <= qpos;
;         if (MODE == M_WIN) valid = valid && (key > qpos - 512);
;         if (MODE == M_SLC) valid = valid && selbit;
;         float v = S[r] * c2;
;         if (MODE == M_FOX) v += (cq - ck[r]) * LOG2E;
;         t[r] = valid ? v : -__builtin_inff();
;         tmax = fmaxf(tmax, t[r]);
;       }
;     }
;     ...
;   bf16x8 pb[2];
; #pragma unroll
;   for (int m = 0; m < 2; ++m) {
;     uint4 u; u.x = cvtpk_asm(pr[8 * m + 0], pr[8 * m + 1]); u.y = cvtpk_asm(pr[8 * m + 2], pr[8 * m + 3]);
;     u.z = cvtpk_asm(pr[8 * m + 4], pr[8 * m + 5]); u.w = cvtpk_asm(pr[8 * m + 6], pr[8 * m + 7]);
;     pb[m] = *(bf16x8*)&u;
;   }
;   if (MODE != M_CMP3) {
;     const char* vp = st + 16384 + r32 * 128;
;     const int vkey = (r32 >> 1) & 7;
; #pragma unroll
;     for (int dt = 0; dt < 4; ++dt)
; #pragma unroll
;       for (int m = 0; m < 2; ++m) {
;         bf16x8 vf = *(const bf16x8*)(vp + dt * 32 * 128 + (((kh * 4 + m * 2 + hh) ^ vkey) << 4));
;         s.o[dt] = mfma(vf, pb[m], s.o[dt]);
;       }
.LBB0_366:
	v_add_u32_e32 v159, s11, v147
	v_cvt_pk_bf16_f32 v85, v4, v5
	v_cvt_pk_bf16_f32 v5, v12, v13
	v_add_u32_e32 v12, v159, v149
	v_cvt_pk_bf16_f32 v87, v8, v9
	v_cvt_pk_bf16_f32 v4, v10, v11
	ds_read_b128 v[8:11], v12 offset:16384
	v_add_u32_e32 v13, v159, v154
	v_cvt_pk_bf16_f32 v84, v80, v81
	v_cvt_pk_bf16_f32 v86, v6, v7
	v_cvt_pk_bf16_f32 v6, v14, v15
	v_cvt_pk_bf16_f32 v7, v82, v83
	s_or_b32 s6, s10, 63
	s_waitcnt lgkmcnt(0)
	v_mfma_f32_32x32x16_bf16 v[64:79], v[8:11], v[84:87], v[64:79]
	ds_read_b128 v[8:11], v13 offset:16384
	v_cmp_le_i32_e32 vcc, s6, v176
	s_waitcnt lgkmcnt(0)
	v_mfma_f32_32x32x16_bf16 v[64:79], v[8:11], v[4:7], v[64:79]
	ds_read_b128 v[8:11], v12 offset:20480
	s_waitcnt lgkmcnt(0)
	v_mfma_f32_32x32x16_bf16 v[48:63], v[8:11], v[84:87], v[48:63]
	ds_read_b128 v[8:11], v13 offset:20480
	s_waitcnt lgkmcnt(0)
	v_mfma_f32_32x32x16_bf16 v[48:63], v[8:11], v[4:7], v[48:63]
	ds_read_b128 v[8:11], v12 offset:24576
	s_waitcnt lgkmcnt(0)
	v_mfma_f32_32x32x16_bf16 v[32:47], v[8:11], v[84:87], v[32:47]
	ds_read_b128 v[8:11], v13 offset:24576
	s_waitcnt lgkmcnt(0)
	v_mfma_f32_32x32x16_bf16 v[32:47], v[8:11], v[4:7], v[32:47]
	ds_read_b128 v[8:11], v12 offset:28672
	s_waitcnt lgkmcnt(0)
	v_mfma_f32_32x32x16_bf16 v[16:31], v[8:11], v[84:87], v[16:31]
	ds_read_b128 v[8:11], v13 offset:28672
	s_waitcnt lgkmcnt(0)
	v_mfma_f32_32x32x16_bf16 v[16:31], v[8:11], v[4:7], v[16:31]
	ds_read_b128 v[4:7], v117 offset:4096
	s_waitcnt lgkmcnt(0)
	v_mfma_f32_32x32x16_bf16 v[80:95], v[4:7], v[96:99], 0
	ds_read_b128 v[4:7], v116 offset:4096
	s_waitcnt lgkmcnt(0)
	v_mfma_f32_32x32x16_bf16 v[80:95], v[4:7], v[100:103], v[80:95]
	ds_read_b128 v[4:7], v161 offset:4096
	s_waitcnt lgkmcnt(0)
	v_mfma_f32_32x32x16_bf16 v[80:95], v[4:7], v[104:107], v[80:95]
	ds_read_b128 v[4:7], v162 offset:4096
	s_waitcnt lgkmcnt(0)
	v_mfma_f32_32x32x16_bf16 v[80:95], v[4:7], v[108:111], v[80:95]
	s_and_saveexec_b64 s[6:7], vcc
	s_xor_b64 s[6:7], exec, s[6:7]
	s_cbranch_execz .LBB0_368
	s_nop 8
	v_mul_f32_e32 v4, s88, v80
	v_mul_f32_e32 v5, s88, v81
	v_mul_f32_e32 v6, s88, v82
	v_mul_f32_e32 v7, s88, v83
	v_max3_f32 v8, v4, s89, v5
	v_max3_f32 v10, v8, v6, v7
	v_mul_f32_e32 v8, s88, v84
	v_mul_f32_e32 v9, s88, v85
	v_mul_f32_e32 v114, s88, v92
	v_mul_f32_e32 v115, s88, v93
	v_max3_f32 v12, v10, v8, v9
	v_mul_f32_e32 v10, s88, v86
	v_mul_f32_e32 v11, s88, v87
	v_mul_f32_e32 v116, s88, v94
	v_mul_f32_e32 v117, s88, v95
	v_max3_f32 v14, v12, v10, v11
	v_mul_f32_e32 v12, s88, v88
	v_mul_f32_e32 v13, s88, v89
	s_nop 0
	v_max3_f32 v80, v14, v12, v13
	v_mul_f32_e32 v14, s88, v90
	v_mul_f32_e32 v15, s88, v91
	s_nop 0
	v_max3_f32 v80, v80, v14, v15
	v_max3_f32 v80, v80, v114, v115
	v_max3_f32 v161, v80, v116, v117
.LBB0_368:
	s_andn2_saveexec_b64 s[6:7], s[6:7]
	s_cbranch_execz .LBB0_370
	v_or_b32_e32 v5, 32, v160
	s_nop 5
	v_mul_f32_e32 v4, 0x3e38aa3b, v80
	v_cmp_le_i32_e32 vcc, v5, v152
	v_mul_f32_e32 v6, 0x3e38aa3b, v81
	v_or_b32_e32 v9, 35, v160
	v_cndmask_b32_e32 v4, v210, v4, vcc
	v_cmp_lt_i32_e32 vcc, v5, v152
	v_or_b32_e32 v10, 34, v160
	v_or_b32_e32 v11, 37, v160
	v_cndmask_b32_e32 v5, v210, v6, vcc
	v_mul_f32_e32 v6, s88, v82
	v_mul_f32_e32 v7, s88, v83
	v_cmp_le_i32_e32 vcc, v9, v113
	v_max3_f32 v8, v4, s89, v5
	v_or_b32_e32 v12, 36, v160
	v_cndmask_b32_e32 v7, v210, v7, vcc
	v_cmp_le_i32_e32 vcc, v10, v112
	v_or_b32_e32 v13, 39, v160
	v_or_b32_e32 v14, 38, v160
	v_cndmask_b32_e32 v6, v210, v6, vcc
	v_max3_f32 v10, v8, v6, v7
	v_mul_f32_e32 v8, s88, v84
	v_mul_f32_e32 v9, s88, v85
	v_cmp_le_i32_e32 vcc, v11, v113
	v_or_b32_e32 v15, 49, v160
	v_or_b32_e32 v80, 48, v160
	v_cndmask_b32_e32 v9, v210, v9, vcc
	v_cmp_le_i32_e32 vcc, v12, v112
	v_or_b32_e32 v81, 51, v160
	v_or_b32_e32 v82, 50, v160
	v_cndmask_b32_e32 v8, v210, v8, vcc
	v_max3_f32 v12, v10, v8, v9
	v_mul_f32_e32 v10, s88, v86
	v_mul_f32_e32 v11, s88, v87
	v_cmp_le_i32_e32 vcc, v13, v113
	v_or_b32_e32 v83, 53, v160
	v_or_b32_e32 v84, 52, v160
	v_cndmask_b32_e32 v11, v210, v11, vcc
	v_cmp_le_i32_e32 vcc, v14, v112
	s_nop 1
	v_cndmask_b32_e32 v10, v210, v10, vcc
	v_max3_f32 v14, v12, v10, v11
	v_mul_f32_e32 v12, s88, v88
	v_mul_f32_e32 v13, s88, v89
	v_cmp_le_i32_e32 vcc, v15, v113
	s_nop 1
	v_cndmask_b32_e32 v13, v210, v13, vcc
	v_cmp_le_i32_e32 vcc, v80, v112
	s_nop 1
	v_cndmask_b32_e32 v12, v210, v12, vcc
	v_max3_f32 v80, v14, v12, v13
	v_mul_f32_e32 v14, s88, v90
	v_mul_f32_e32 v15, s88, v91
	v_cmp_le_i32_e32 vcc, v81, v113
	s_nop 1
	v_cndmask_b32_e32 v15, v210, v15, vcc
	v_cmp_le_i32_e32 vcc, v82, v112
	s_nop 1
	v_cndmask_b32_e32 v14, v210, v14, vcc
	v_max3_f32 v82, v80, v14, v15
	v_mul_f32_e32 v80, s88, v92
	v_mul_f32_e32 v81, s88, v93
	v_cmp_le_i32_e32 vcc, v83, v113
	v_or_b32_e32 v83, 55, v160
	s_nop 0
	v_cndmask_b32_e32 v115, v210, v81, vcc
	v_cmp_le_i32_e32 vcc, v84, v112
	v_or_b32_e32 v84, 54, v160
	s_nop 0
	v_cndmask_b32_e32 v114, v210, v80, vcc
	v_mul_f32_e32 v80, s88, v94
	v_mul_f32_e32 v81, s88, v95
	v_cmp_le_i32_e32 vcc, v83, v113
	v_max3_f32 v82, v82, v114, v115
	s_nop 0
	v_cndmask_b32_e32 v117, v210, v81, vcc
	v_cmp_le_i32_e32 vcc, v84, v112
	s_nop 1
	v_cndmask_b32_e32 v116, v210, v80, vcc
	v_max3_f32 v161, v82, v116, v117

; DEV f32x16 mfma(bf16x8 a, bf16x8 b, f32x16 c) { return __builtin_amdgcn_mfma_f32_32x32x16_bf16(a, b, c, 0, 0, 0); }
; template <int MODE, int DQK>
; DEV void flash_half(FlashState& s, f32x16* imp, const bf16x8* qf, const char* st, int kh, int kb, int qpos, float cq,
;                     const float* __restrict__ cumk, bool selbit, float c2, float invl, int r32, int hh, int wqmin_, int wqmax_) {
;     ...
;   for (int ks = 0; ks < DQK / 16; ++ks) { bf16x8 kf = *(const bf16x8*)(kp + (((ks * 2 + hh) ^ kkey) << 4)); S = mfma(kf, qf[ks], S); }
;     ...
;     if (MODE == M_FOX) {
;       const float* cl = (const float*)(st + 32768) + kh * 32 + 8 * hh;
;       float4 a0 = *(const float4*)(cl), a1 = *(const float4*)(cl + 4);
;       float4 a2 = *(const float4*)(cl + 16), a3 = *(const float4*)(cl + 20);
;       ck[0] = a0.x; ck[1] = a0.y; ck[2] = a0.z; ck[3] = a0.w; ck[4] = a1.x; ck[5] = a1.y; ck[6] = a1.z; ck[7] = a1.w;
;       ck[8] = a2.x; ck[9] = a2.y; ck[10] = a2.z; ck[11] = a2.w; ck[12] = a3.x; ck[13] = a3.y; ck[14] = a3.z; ck[15] = a3.w;
;     }
;     float tmax = -__builtin_inff();
;     bool nomask = (kb + 31 <= wqmin_);
;     if (MODE == M_WIN) nomask = nomask && (kb > wqmax_ - 512);
;     if (MODE == M_SLC) nomask = nomask && __all(selbit);
;     if (MODE == M_CMP1 || MODE == M_CMP2 || MODE == M_CMP3) nomask = false;
;     if (nomask) {
; #pragma unroll
;       for (int r = 0; r < 16; ++r) {
;         float v = S[r] * c2;
;         if (MODE == M_FOX) v += (cq - ck[r]) * LOG2E;
;         t[r] = v;
;         tmax = fmaxf(tmax, v);
;       }
;     } else {
; #pragma unroll
;       for (int r = 0; r < 16; ++r) {
;         int key = kbase + r + (r >= 8 ? 8 : 0);
;         bool valid = key <= qpos;
;         if (MODE == M_WIN) valid = valid && (key > qpos - 512);
;         if (MODE == M_SLC) valid = valid && selbit;
;         float v = S[r] * c2;
;         if (MODE == M_FOX) v += (cq - ck[r]) * LOG2E;
;         t[r] = valid ? v : -__builtin_inff();
;         tmax = fmaxf(tmax, t[r]);
;       }
;     }
.LBB0_393:
	s_mov_b32 s6, 0x8100
	s_lshl_b32 s12, s12, 6
	v_mul_lo_u32 v1, v225, s6
	v_cmp_le_i32_e32 vcc, s12, v186
	s_and_saveexec_b64 s[24:25], vcc
	s_cbranch_execz .LBB0_409
	v_add_u32_e32 v10, v1, v187
	v_add_u32_e32 v226, v10, v188
	ds_read_b128 v[2:5], v226 offset:8192
	v_add_u32_e32 v175, v10, v189
	ds_read_b128 v[6:9], v175 offset:8192
	v_add_u32_e32 v227, v10, v190
	v_add_u32_e32 v228, v10, v191
	v_add_u32_e32 v229, v10, v214
	v_add_u32_e32 v230, v10, v215
	v_add_u32_e32 v232, v10, v216
	v_add_u32_e32 v231, v10, v217
	s_waitcnt lgkmcnt(1)
	v_mfma_f32_32x32x16_bf16 v[80:95], v[2:5], v[96:99], 0
	ds_read_b128 v[2:5], v227 offset:8192
	v_lshl_add_u32 v147, v218, 2, v1
	s_or_b32 s6, s12, 63
	v_cmp_le_i32_e32 vcc, s6, v176
	s_waitcnt lgkmcnt(1)
	v_mfma_f32_32x32x16_bf16 v[80:95], v[6:9], v[100:103], v[80:95]
	ds_read_b128 v[6:9], v228 offset:8192
	s_waitcnt lgkmcnt(1)
	v_mfma_f32_32x32x16_bf16 v[80:95], v[2:5], v[104:107], v[80:95]
	ds_read_b128 v[2:5], v229 offset:8192
	s_waitcnt lgkmcnt(1)
	v_mfma_f32_32x32x16_bf16 v[80:95], v[6:9], v[108:111], v[80:95]
	ds_read_b128 v[6:9], v230 offset:8192
	s_waitcnt lgkmcnt(1)
	v_mfma_f32_32x32x16_bf16 v[80:95], v[2:5], v[112:115], v[80:95]
	ds_read_b128 v[2:5], v232 offset:8192
	s_waitcnt lgkmcnt(1)
	v_mfma_f32_32x32x16_bf16 v[80:95], v[6:9], v[116:119], v[80:95]
	ds_read_b128 v[6:9], v231 offset:8192
	s_waitcnt lgkmcnt(1)
	v_mfma_f32_32x32x16_bf16 v[80:95], v[2:5], v[120:123], v[80:95]
	ds_read_b128 v[2:5], v147 offset:32896
	ds_read_b128 v[10:13], v147 offset:32912
	ds_read_b128 v[156:159], v147 offset:32960
	ds_read_b128 v[160:163], v147 offset:32976
	s_waitcnt lgkmcnt(3)
	v_pk_add_f32 v[172:173], v[154:155], v[4:5] neg_lo:[0,1] neg_hi:[0,1]
	s_waitcnt lgkmcnt(2)
	v_pk_add_f32 v[170:171], v[154:155], v[10:11] neg_lo:[0,1] neg_hi:[0,1]
	v_pk_add_f32 v[168:169], v[154:155], v[12:13] neg_lo:[0,1] neg_hi:[0,1]
	s_waitcnt lgkmcnt(1)
	v_pk_add_f32 v[166:167], v[154:155], v[156:157] neg_lo:[0,1] neg_hi:[0,1]
	v_pk_add_f32 v[164:165], v[154:155], v[158:159] neg_lo:[0,1] neg_hi:[0,1]
	v_mfma_f32_32x32x16_bf16 v[80:95], v[6:9], v[124:127], v[80:95]
	s_waitcnt lgkmcnt(0)
	v_add_f32_e64 v160, v154, -v160
	v_add_f32_e64 v161, v155, -v161
	v_add_f32_e64 v156, v154, -v162
	v_add_f32_e64 v157, v155, -v163
	s_and_saveexec_b64 s[6:7], vcc
	s_xor_b64 s[6:7], exec, s[6:7]
	s_cbranch_execz .LBB0_396
	v_pk_add_f32 v[2:3], v[154:155], v[2:3] neg_lo:[0,1] neg_hi:[0,1]
	s_mov_b32 s10, 0x3fb8aa3b
	v_mul_f32_e32 v2, s10, v2
	v_mul_f32_e32 v3, s10, v3
	s_nop 0
	v_pk_fma_f32 v[4:5], v[80:81], s[96:97], v[2:3] op_sel_hi:[1,0,1]
	v_mul_f32_e32 v2, s10, v172
	v_mul_f32_e32 v3, s10, v173
	v_max3_f32 v8, v4, s89, v5
	v_pk_fma_f32 v[6:7], v[82:83], s[96:97], v[2:3] op_sel_hi:[1,0,1]
	v_mul_f32_e32 v2, s10, v170
	v_mul_f32_e32 v3, s10, v171
	v_max3_f32 v10, v8, v6, v7
	v_pk_fma_f32 v[8:9], v[84:85], s[96:97], v[2:3] op_sel_hi:[1,0,1]
	v_mul_f32_e32 v2, s10, v168
	v_mul_f32_e32 v3, s10, v169
	v_max3_f32 v12, v10, v8, v9
	v_pk_fma_f32 v[10:11], v[86:87], s[96:97], v[2:3] op_sel_hi:[1,0,1]
	v_mul_f32_e32 v2, s10, v166
	v_mul_f32_e32 v3, s10, v167
	v_max3_f32 v14, v12, v10, v11
	v_pk_fma_f32 v[12:13], v[88:89], s[96:97], v[2:3] op_sel_hi:[1,0,1]
	v_mul_f32_e32 v2, s10, v164
	v_mul_f32_e32 v3, s10, v165
	v_max3_f32 v80, v14, v12, v13
	v_pk_fma_f32 v[14:15], v[90:91], s[96:97], v[2:3] op_sel_hi:[1,0,1]
	v_mul_f32_e32 v2, s10, v160
	v_mul_f32_e32 v3, s10, v161
	v_max3_f32 v80, v80, v14, v15
	v_pk_fma_f32 v[158:159], v[92:93], s[96:97], v[2:3] op_sel_hi:[1,0,1]
	v_mul_f32_e32 v2, s10, v156
	v_mul_f32_e32 v3, s10, v157
	v_max3_f32 v80, v80, v158, v159
	v_pk_fma_f32 v[162:163], v[94:95], s[96:97], v[2:3] op_sel_hi:[1,0,1]
	s_nop 0
	v_max3_f32 v143, v80, v162, v163
.LBB0_396:
	s_or_saveexec_b64 s[6:7], s[6:7]
	v_or_b32_e32 v149, s12, v218
	s_xor_b64 exec, exec, s[6:7]
	s_cbranch_execz .LBB0_398
	s_mov_b32 s10, 0x3fb8aa3b
	v_sub_f32_e32 v5, v154, v2
	v_mov_b32_e32 v4, v80
	s_mov_b32 s97, s10
	v_mul_f32_e32 v2, 0x3e0293ee, v80
	v_pk_fma_f32 v[6:7], v[4:5], s[96:97], v[2:3] op_sel_hi:[1,1,0]
	v_sub_f32_e32 v3, v154, v3
	v_or_b32_e32 v8, 32, v149
	v_mov_b32_e32 v2, v81
	v_mul_f32_e32 v4, 0x3fb8aa3b, v3
	v_pk_fma_f32 v[2:3], v[2:3], s[96:97], v[4:5] op_sel_hi:[1,1,0]
	v_cmp_lt_i32_e32 vcc, v8, v141
	v_or_b32_e32 v6, 34, v149
	v_or_b32_e32 v9, 37, v149
	v_cndmask_b32_e32 v5, v210, v2, vcc
	v_cmp_ge_i32_e32 vcc, v141, v8
	v_mul_f32_e32 v2, s10, v172
	v_mul_f32_e32 v3, s10, v173
	v_or_b32_e32 v11, 39, v149
	v_cndmask_b32_e32 v4, v210, v7, vcc
	v_or_b32_e32 v7, 35, v149
	v_pk_fma_f32 v[2:3], v[82:83], s[96:97], v[2:3] op_sel_hi:[1,0,1]
	v_cmp_le_i32_e32 vcc, v6, v152
	v_max3_f32 v8, v4, s89, v5
	v_or_b32_e32 v13, 49, v149
	v_cndmask_b32_e32 v6, v210, v2, vcc
	v_cmp_le_i32_e32 vcc, v7, v133
	v_or_b32_e32 v15, 51, v149
	v_or_b32_e32 v82, 52, v149
	v_cndmask_b32_e32 v7, v210, v3, vcc
	v_max3_f32 v10, v8, v6, v7
	v_or_b32_e32 v8, 36, v149
	v_mul_f32_e32 v2, s10, v170
	v_mul_f32_e32 v3, s10, v171
	v_cmp_le_i32_e32 vcc, v8, v152
	v_pk_fma_f32 v[2:3], v[84:85], s[96:97], v[2:3] op_sel_hi:[1,0,1]
	v_or_b32_e32 v81, 53, v149
	v_cndmask_b32_e32 v8, v210, v2, vcc
	v_cmp_le_i32_e32 vcc, v9, v133
	s_nop 1
	v_cndmask_b32_e32 v9, v210, v3, vcc
	v_max3_f32 v12, v10, v8, v9
	v_or_b32_e32 v10, 38, v149
	v_mul_f32_e32 v2, s10, v168
	v_mul_f32_e32 v3, s10, v169
	v_cmp_le_i32_e32 vcc, v10, v152
	v_pk_fma_f32 v[2:3], v[86:87], s[96:97], v[2:3] op_sel_hi:[1,0,1]
	s_nop 0
	v_cndmask_b32_e32 v10, v210, v2, vcc
	v_cmp_le_i32_e32 vcc, v11, v133
	s_nop 1
	v_cndmask_b32_e32 v11, v210, v3, vcc
	v_max3_f32 v14, v12, v10, v11
	v_or_b32_e32 v12, 48, v149
	v_mul_f32_e32 v2, s10, v166
	v_mul_f32_e32 v3, s10, v167
	v_cmp_le_i32_e32 vcc, v12, v152
	v_pk_fma_f32 v[2:3], v[88:89], s[96:97], v[2:3] op_sel_hi:[1,0,1]
	s_nop 0
	v_cndmask_b32_e32 v12, v210, v2, vcc
	v_cmp_le_i32_e32 vcc, v13, v133
	s_nop 1
	v_cndmask_b32_e32 v13, v210, v3, vcc
	v_max3_f32 v80, v14, v12, v13
	v_or_b32_e32 v14, 50, v149
	v_mul_f32_e32 v2, s10, v164
	v_mul_f32_e32 v3, s10, v165
	v_cmp_le_i32_e32 vcc, v14, v152
	v_pk_fma_f32 v[2:3], v[90:91], s[96:97], v[2:3] op_sel_hi:[1,0,1]
	s_nop 0
	v_cndmask_b32_e32 v14, v210, v2, vcc
	v_cmp_le_i32_e32 vcc, v15, v133
	s_nop 1
	v_cndmask_b32_e32 v15, v210, v3, vcc
	v_mul_f32_e32 v2, s10, v160
	v_mul_f32_e32 v3, s10, v161
	v_cmp_le_i32_e32 vcc, v82, v152
	v_pk_fma_f32 v[2:3], v[92:93], s[96:97], v[2:3] op_sel_hi:[1,0,1]
	v_or_b32_e32 v82, 54, v149
	v_cndmask_b32_e32 v158, v210, v2, vcc
	v_cmp_le_i32_e32 vcc, v81, v133
	v_or_b32_e32 v81, 55, v149
	v_max3_f32 v80, v80, v14, v15
	v_cndmask_b32_e32 v159, v210, v3, vcc
	v_mul_f32_e32 v2, s10, v156
	v_mul_f32_e32 v3, s10, v157
	v_cmp_le_i32_e32 vcc, v82, v152
	v_pk_fma_f32 v[2:3], v[94:95], s[96:97], v[2:3] op_sel_hi:[1,0,1]
	v_max3_f32 v80, v80, v158, v159
	v_cndmask_b32_e32 v162, v210, v2, vcc
	v_cmp_le_i32_e32 vcc, v81, v133
	s_nop 1
	v_cndmask_b32_e32 v163, v210, v3, vcc
	v_max3_f32 v143, v80, v162, v163

; DEV unsigned cvtpk_asm(float lo, float hi) { unsigned r; asm("v_cvt_pk_bf16_f32 %0, %1, %2" : "=v"(r) : "v"(lo), "v"(hi)); return r; }
; DEV f32x16 mfma(bf16x8 a, bf16x8 b, f32x16 c) { return __builtin_amdgcn_mfma_f32_32x32x16_bf16(a, b, c, 0, 0, 0); }
; template <int MODE, int DQK>
; DEV void flash_half(FlashState& s, f32x16* imp, const bf16x8* qf, const char* st, int kh, int kb, int qpos, float cq,
;                     const float* __restrict__ cumk, bool selbit, float c2, float invl, int r32, int hh, int wqmin_, int wqmax_) {
;     ...
;   for (int ks = 0; ks < DQK / 16; ++ks) { bf16x8 kf = *(const bf16x8*)(kp + (((ks * 2 + hh) ^ kkey) << 4)); S = mfma(kf, qf[ks], S); }
;     ...
;     if (MODE == M_FOX) {
;       const float* cl = (const float*)(st + 32768) + kh * 32 + 8 * hh;
;       float4 a0 = *(const float4*)(cl), a1 = *(const float4*)(cl + 4);
;       float4 a2 = *(const float4*)(cl + 16), a3 = *(const float4*)(cl + 20);
;       ck[0] = a0.x; ck[1] = a0.y; ck[2] = a0.z; ck[3] = a0.w; ck[4] = a1.x; ck[5] = a1.y; ck[6] = a1.z; ck[7] = a1.w;
;       ck[8] = a2.x; ck[9] = a2.y; ck[10] = a2.z; ck[11] = a2.w; ck[12] = a3.x; ck[13] = a3.y; ck[14] = a3.z; ck[15] = a3.w;
;     }
;     float tmax = -__builtin_inff();
;     bool nomask = (kb + 31 <= wqmin_);
;     if (MODE == M_WIN) nomask = nomask && (kb > wqmax_ - 512);
;     if (MODE == M_SLC) nomask = nomask && __all(selbit);
;     if (MODE == M_CMP1 || MODE == M_CMP2 || MODE == M_CMP3) nomask = false;
;     if (nomask) {
; #pragma unroll
;       for (int r = 0; r < 16; ++r) {
;         float v = S[r] * c2;
;         if (MODE == M_FOX) v += (cq - ck[r]) * LOG2E;
;         t[r] = v;
;         tmax = fmaxf(tmax, v);
;     ...
;   bf16x8 pb[2];
; #pragma unroll
;   for (int m = 0; m < 2; ++m) {
;     uint4 u; u.x = cvtpk_asm(pr[8 * m + 0], pr[8 * m + 1]); u.y = cvtpk_asm(pr[8 * m + 2], pr[8 * m + 3]);
;     u.z = cvtpk_asm(pr[8 * m + 4], pr[8 * m + 5]); u.w = cvtpk_asm(pr[8 * m + 6], pr[8 * m + 7]);
;     pb[m] = *(bf16x8*)&u;
;   }
;   if (MODE != M_CMP3) {
;     const char* vp = st + 16384 + r32 * 128;
;     const int vkey = (r32 >> 1) & 7;
; #pragma unroll
;     for (int dt = 0; dt < 4; ++dt)
; #pragma unroll
;       for (int m = 0; m < 2; ++m) {
;         bf16x8 vf = *(const bf16x8*)(vp + dt * 32 * 128 + (((kh * 4 + m * 2 + hh) ^ vkey) << 4));
;         s.o[dt] = mfma(vf, pb[m], s.o[dt]);
;       }
.LBB0_401:
	v_add_u32_e32 v145, v1, v219
	v_cvt_pk_bf16_f32 v2, v2, v3
	v_cvt_pk_bf16_f32 v3, v4, v5
	v_cvt_pk_bf16_f32 v5, v10, v11
	v_cvt_pk_bf16_f32 v10, v80, v81
	v_add_u32_e32 v80, v145, v220
	v_cvt_pk_bf16_f32 v4, v8, v9
	v_cvt_pk_bf16_f32 v8, v12, v13
	v_cvt_pk_bf16_f32 v9, v14, v15
	ds_read_b128 v[12:15], v80 offset:16384
	v_add_u32_e32 v81, v145, v221
	s_waitcnt lgkmcnt(0)
	v_mfma_f32_32x32x16_bf16 v[64:79], v[12:15], v[2:5], v[64:79]
	ds_read_b128 v[12:15], v81 offset:16384
	v_cvt_pk_bf16_f32 v11, v82, v83
	s_or_b32 s6, s12, 31
	v_cmp_le_i32_e32 vcc, s6, v176
	s_waitcnt lgkmcnt(0)
	v_mfma_f32_32x32x16_bf16 v[64:79], v[12:15], v[8:11], v[64:79]
	ds_read_b128 v[12:15], v80 offset:20480
	s_waitcnt lgkmcnt(0)
	v_mfma_f32_32x32x16_bf16 v[48:63], v[12:15], v[2:5], v[48:63]
	ds_read_b128 v[12:15], v81 offset:20480
	s_waitcnt lgkmcnt(0)
	v_mfma_f32_32x32x16_bf16 v[48:63], v[12:15], v[8:11], v[48:63]
	ds_read_b128 v[12:15], v80 offset:24576
	s_waitcnt lgkmcnt(0)
	v_mfma_f32_32x32x16_bf16 v[32:47], v[12:15], v[2:5], v[32:47]
	ds_read_b128 v[12:15], v81 offset:24576
	s_waitcnt lgkmcnt(0)
	v_mfma_f32_32x32x16_bf16 v[32:47], v[12:15], v[8:11], v[32:47]
	ds_read_b128 v[12:15], v80 offset:28672
	s_waitcnt lgkmcnt(0)
	v_mfma_f32_32x32x16_bf16 v[16:31], v[12:15], v[2:5], v[16:31]
	ds_read_b128 v[2:5], v81 offset:28672
	s_waitcnt lgkmcnt(0)
	v_mfma_f32_32x32x16_bf16 v[16:31], v[2:5], v[8:11], v[16:31]
	ds_read_b128 v[2:5], v226
	s_waitcnt lgkmcnt(0)
	v_mfma_f32_32x32x16_bf16 v[80:95], v[2:5], v[96:99], 0
	ds_read_b128 v[2:5], v175
	s_waitcnt lgkmcnt(0)
	v_mfma_f32_32x32x16_bf16 v[80:95], v[2:5], v[100:103], v[80:95]
	ds_read_b128 v[2:5], v227
	s_waitcnt lgkmcnt(0)
	v_mfma_f32_32x32x16_bf16 v[80:95], v[2:5], v[104:107], v[80:95]
	ds_read_b128 v[2:5], v228
	s_waitcnt lgkmcnt(0)
	v_mfma_f32_32x32x16_bf16 v[80:95], v[2:5], v[108:111], v[80:95]
	ds_read_b128 v[2:5], v229
	s_waitcnt lgkmcnt(0)
	v_mfma_f32_32x32x16_bf16 v[80:95], v[2:5], v[112:115], v[80:95]
	ds_read_b128 v[2:5], v230
	s_waitcnt lgkmcnt(0)
	v_mfma_f32_32x32x16_bf16 v[80:95], v[2:5], v[116:119], v[80:95]
	ds_read_b128 v[2:5], v232
	s_waitcnt lgkmcnt(0)
	v_mfma_f32_32x32x16_bf16 v[80:95], v[2:5], v[120:123], v[80:95]
	ds_read_b128 v[2:5], v231
	s_waitcnt lgkmcnt(0)
	v_mfma_f32_32x32x16_bf16 v[80:95], v[2:5], v[124:127], v[80:95]
	ds_read_b128 v[2:5], v147 offset:32768
	ds_read_b128 v[8:11], v147 offset:32784
	ds_read_b128 v[12:15], v147 offset:32832
	ds_read_b128 v[156:159], v147 offset:32848
	s_waitcnt lgkmcnt(3)
	v_pk_add_f32 v[174:175], v[154:155], v[4:5] neg_lo:[0,1] neg_hi:[0,1]
	s_waitcnt lgkmcnt(2)
	v_pk_add_f32 v[172:173], v[154:155], v[8:9] neg_lo:[0,1] neg_hi:[0,1]
	v_pk_add_f32 v[170:171], v[154:155], v[10:11] neg_lo:[0,1] neg_hi:[0,1]
	s_waitcnt lgkmcnt(1)
	v_pk_add_f32 v[168:169], v[154:155], v[12:13] neg_lo:[0,1] neg_hi:[0,1]
	v_pk_add_f32 v[166:167], v[154:155], v[14:15] neg_lo:[0,1] neg_hi:[0,1]
	s_waitcnt lgkmcnt(0)
	v_pk_add_f32 v[162:163], v[154:155], v[156:157] neg_lo:[0,1] neg_hi:[0,1]
	v_pk_add_f32 v[158:159], v[154:155], v[158:159] neg_lo:[0,1] neg_hi:[0,1]
	s_and_saveexec_b64 s[6:7], vcc
	s_xor_b64 s[6:7], exec, s[6:7]
	s_cbranch_execz .LBB0_403
	v_pk_add_f32 v[2:3], v[154:155], v[2:3] neg_lo:[0,1] neg_hi:[0,1]
	s_mov_b32 s12, 0x3fb8aa3b
	v_mul_f32_e32 v2, s12, v2
	v_mul_f32_e32 v3, s12, v3
	s_nop 0
	v_pk_fma_f32 v[4:5], v[80:81], s[96:97], v[2:3] op_sel_hi:[1,0,1]
	v_mul_f32_e32 v2, s12, v174
	v_mul_f32_e32 v3, s12, v175
	v_max3_f32 v10, v4, s89, v5
	v_pk_fma_f32 v[8:9], v[82:83], s[96:97], v[2:3] op_sel_hi:[1,0,1]
	v_mul_f32_e32 v2, s12, v172
	v_mul_f32_e32 v3, s12, v173
	v_max3_f32 v12, v10, v8, v9
	v_pk_fma_f32 v[10:11], v[84:85], s[96:97], v[2:3] op_sel_hi:[1,0,1]
	v_mul_f32_e32 v2, s12, v170
	v_mul_f32_e32 v3, s12, v171
	v_max3_f32 v14, v12, v10, v11
	v_pk_fma_f32 v[12:13], v[86:87], s[96:97], v[2:3] op_sel_hi:[1,0,1]
	v_mul_f32_e32 v2, s12, v168
	v_mul_f32_e32 v3, s12, v169
	v_max3_f32 v80, v14, v12, v13
	v_pk_fma_f32 v[14:15], v[88:89], s[96:97], v[2:3] op_sel_hi:[1,0,1]
	v_mul_f32_e32 v2, s12, v166
	v_mul_f32_e32 v3, s12, v167
	v_max3_f32 v80, v80, v14, v15
	v_pk_fma_f32 v[156:157], v[90:91], s[96:97], v[2:3] op_sel_hi:[1,0,1]
	v_mul_f32_e32 v2, s12, v162
	v_mul_f32_e32 v3, s12, v163
	v_max3_f32 v80, v80, v156, v157
	v_pk_fma_f32 v[160:161], v[92:93], s[96:97], v[2:3] op_sel_hi:[1,0,1]
	v_mul_f32_e32 v2, s12, v158
	v_mul_f32_e32 v3, s12, v159
	v_max3_f32 v80, v80, v160, v161
	v_pk_fma_f32 v[164:165], v[94:95], s[96:97], v[2:3] op_sel_hi:[1,0,1]
	s_nop 0
	v_max3_f32 v147, v80, v164, v165
; template <int MODE, int DQK>
; DEV void flash_half(FlashState& s, f32x16* imp, const bf16x8* qf, const char* st, int kh, int kb, int qpos, float cq,
;                     const float* __restrict__ cumk, bool selbit, float c2, float invl, int r32, int hh, int wqmin_, int wqmax_) {
;     ...
;     } else {
; #pragma unroll
;       for (int r = 0; r < 16; ++r) {
;         int key = kbase + r + (r >= 8 ? 8 : 0);
;         bool valid = key <= qpos;
;         if (MODE == M_WIN) valid = valid && (key > qpos - 512);
;         if (MODE == M_SLC) valid = valid && selbit;
;         float v = S[r] * c2;
;         if (MODE == M_FOX) v += (cq - ck[r]) * LOG2E;
;         t[r] = valid ? v : -__builtin_inff();
;         tmax = fmaxf(tmax, t[r]);
;       }
;     }
.LBB0_403:
	s_andn2_saveexec_b64 s[6:7], s[6:7]
	s_cbranch_execz .LBB0_405
	s_mov_b32 s12, 0x3fb8aa3b
	v_sub_f32_e32 v5, v154, v2
	v_mov_b32_e32 v4, v80
	s_mov_b32 s97, s12
	v_mul_f32_e32 v2, 0x3e0293ee, v80
	v_pk_fma_f32 v[8:9], v[4:5], s[96:97], v[2:3] op_sel_hi:[1,1,0]
	v_sub_f32_e32 v3, v154, v3
	v_mov_b32_e32 v2, v81
	v_mul_f32_e32 v4, 0x3fb8aa3b, v3
	v_pk_fma_f32 v[2:3], v[2:3], s[96:97], v[4:5] op_sel_hi:[1,1,0]
	v_cmp_lt_i32_e32 vcc, v149, v141
	v_or_b32_e32 v8, 2, v149
	v_or_b32_e32 v11, 5, v149
	v_cndmask_b32_e32 v5, v210, v2, vcc
	v_cmp_ge_i32_e32 vcc, v141, v149
	v_mul_f32_e32 v2, s12, v174
	v_mul_f32_e32 v3, s12, v175
	v_or_b32_e32 v13, 7, v149
	v_cndmask_b32_e32 v4, v210, v9, vcc
	v_or_b32_e32 v9, 3, v149
	v_pk_fma_f32 v[2:3], v[82:83], s[96:97], v[2:3] op_sel_hi:[1,0,1]
	v_cmp_le_i32_e32 vcc, v8, v152
	v_max3_f32 v10, v4, s89, v5
	v_or_b32_e32 v15, 17, v149
	v_cndmask_b32_e32 v8, v210, v2, vcc
	v_cmp_le_i32_e32 vcc, v9, v133
	v_or_b32_e32 v82, 18, v149
	v_or_b32_e32 v81, 19, v149
	v_cndmask_b32_e32 v9, v210, v3, vcc
	v_max3_f32 v12, v10, v8, v9
	v_or_b32_e32 v10, 4, v149
	v_mul_f32_e32 v2, s12, v172
	v_mul_f32_e32 v3, s12, v173
	v_cmp_le_i32_e32 vcc, v10, v152
	v_pk_fma_f32 v[2:3], v[84:85], s[96:97], v[2:3] op_sel_hi:[1,0,1]
	s_nop 0
	v_cndmask_b32_e32 v10, v210, v2, vcc
	v_cmp_le_i32_e32 vcc, v11, v133
	s_nop 1
	v_cndmask_b32_e32 v11, v210, v3, vcc
	v_max3_f32 v14, v12, v10, v11
	v_or_b32_e32 v12, 6, v149
	v_mul_f32_e32 v2, s12, v170
	v_mul_f32_e32 v3, s12, v171
	v_cmp_le_i32_e32 vcc, v12, v152
	v_pk_fma_f32 v[2:3], v[86:87], s[96:97], v[2:3] op_sel_hi:[1,0,1]
	s_nop 0
	v_cndmask_b32_e32 v12, v210, v2, vcc
	v_cmp_le_i32_e32 vcc, v13, v133
	s_nop 1
	v_cndmask_b32_e32 v13, v210, v3, vcc
	v_max3_f32 v80, v14, v12, v13
	v_or_b32_e32 v14, 16, v149
	v_mul_f32_e32 v2, s12, v168
	v_mul_f32_e32 v3, s12, v169
	v_cmp_le_i32_e32 vcc, v14, v152
	v_pk_fma_f32 v[2:3], v[88:89], s[96:97], v[2:3] op_sel_hi:[1,0,1]
	s_nop 0
	v_cndmask_b32_e32 v14, v210, v2, vcc
	v_cmp_le_i32_e32 vcc, v15, v133
	s_nop 1
	v_cndmask_b32_e32 v15, v210, v3, vcc
	v_mul_f32_e32 v2, s12, v166
	v_mul_f32_e32 v3, s12, v167
	v_cmp_le_i32_e32 vcc, v82, v152
	v_pk_fma_f32 v[2:3], v[90:91], s[96:97], v[2:3] op_sel_hi:[1,0,1]
	v_or_b32_e32 v82, 20, v149
	v_cndmask_b32_e32 v156, v210, v2, vcc
	v_cmp_le_i32_e32 vcc, v81, v133
	v_or_b32_e32 v81, 21, v149
	v_max3_f32 v80, v80, v14, v15
	v_cndmask_b32_e32 v157, v210, v3, vcc
	v_mul_f32_e32 v2, s12, v162
	v_mul_f32_e32 v3, s12, v163
	v_cmp_le_i32_e32 vcc, v82, v152
	v_pk_fma_f32 v[2:3], v[92:93], s[96:97], v[2:3] op_sel_hi:[1,0,1]
	v_or_b32_e32 v82, 22, v149
	v_cndmask_b32_e32 v160, v210, v2, vcc
	v_cmp_le_i32_e32 vcc, v81, v133
	v_or_b32_e32 v81, 23, v149
	v_max3_f32 v80, v80, v156, v157
	v_cndmask_b32_e32 v161, v210, v3, vcc
	v_mul_f32_e32 v2, s12, v158
	v_mul_f32_e32 v3, s12, v159
	v_cmp_le_i32_e32 vcc, v82, v152
	v_pk_fma_f32 v[2:3], v[94:95], s[96:97], v[2:3] op_sel_hi:[1,0,1]
	v_max3_f32 v80, v80, v160, v161
	v_cndmask_b32_e32 v164, v210, v2, vcc
	v_cmp_le_i32_e32 vcc, v81, v133
	s_nop 1
	v_cndmask_b32_e32 v165, v210, v3, vcc
	v_max3_f32 v147, v80, v164, v165
